# pp_v31 + ATTN LOAD segment: LDS-read throttle lgkmcnt(8) -> lgkmcnt(10) (at most 14 reads outstanding)
# baseline (speedup 1.0000x reference)
.Lpp_hb:
	s_waitcnt lgkmcnt(0)
	s_barrier
	s_cmp_gt_u32 s35, s28
	s_cbranch_scc1 .Lpp_skip
	v_add_u32_e32 v149, s5, v140
	v_add_u32_e32 v150, s5, v141
	v_add_u32_sdwa v230, v4, s25 dst_sel:DWORD dst_unused:UNUSED_PAD src0_sel:BYTE_0 src1_sel:DWORD
	v_add_u32_sdwa v231, v4, s25 dst_sel:DWORD dst_unused:UNUSED_PAD src0_sel:BYTE_1 src1_sel:DWORD
	v_add_u32_sdwa v232, v4, s25 dst_sel:DWORD dst_unused:UNUSED_PAD src0_sel:BYTE_2 src1_sel:DWORD
	v_add_u32_sdwa v233, v4, s25 dst_sel:DWORD dst_unused:UNUSED_PAD src0_sel:BYTE_3 src1_sel:DWORD
	v_add_u32_sdwa v234, v3, s25 dst_sel:DWORD dst_unused:UNUSED_PAD src0_sel:BYTE_0 src1_sel:DWORD
	v_add_u32_sdwa v235, v3, s25 dst_sel:DWORD dst_unused:UNUSED_PAD src0_sel:BYTE_1 src1_sel:DWORD
	v_add_u32_sdwa v236, v3, s25 dst_sel:DWORD dst_unused:UNUSED_PAD src0_sel:BYTE_2 src1_sel:DWORD
	v_add_u32_sdwa v237, v3, s25 dst_sel:DWORD dst_unused:UNUSED_PAD src0_sel:BYTE_3 src1_sel:DWORD
	ds_read_b128 v[66:69], v230
	ds_read_b128 v[70:73], v231
	ds_read_b128 v[74:77], v232
	ds_read_b128 v[78:81], v233
	ds_read_b128 v[182:185], v149
	ds_read_b128 v[186:189], v149 offset:2048
	ds_read_b128 v[190:193], v149 offset:4096
	ds_read_b128 v[194:197], v149 offset:6144
	ds_read_b128 v[82:85], v234
	ds_read_b128 v[86:89], v235
	ds_read_b128 v[90:93], v236
	ds_read_b128 v[94:97], v237
	s_waitcnt lgkmcnt(10)
	ds_read_b128 v[198:201], v149 offset:512
	ds_read_b128 v[202:205], v149 offset:2560
	ds_read_b128 v[206:209], v149 offset:4608
	ds_read_b128 v[210:213], v149 offset:6656
	s_waitcnt lgkmcnt(10)
	ds_read_b64_tr_b16 v[152:153], v150
	ds_read_b64_tr_b16 v[154:155], v150 offset:512
	ds_read_b64_tr_b16 v[156:157], v150 offset:1024
	ds_read_b64_tr_b16 v[158:159], v150 offset:1536
	s_waitcnt lgkmcnt(10)
	ds_read_b64_tr_b16 v[160:161], v150 offset:2048
	ds_read_b64_tr_b16 v[162:163], v150 offset:2560
	ds_read_b64_tr_b16 v[164:165], v150 offset:3072
	ds_read_b64_tr_b16 v[166:167], v150 offset:3584
	s_waitcnt lgkmcnt(10)
	ds_read_b64_tr_b16 v[168:169], v150 offset:4096
	ds_read_b64_tr_b16 v[170:171], v150 offset:4608
	ds_read_b64_tr_b16 v[172:173], v150 offset:5120
	ds_read_b64_tr_b16 v[174:175], v150 offset:5632
	s_waitcnt lgkmcnt(10)
	ds_read_b64_tr_b16 v[214:215], v150 offset:6144
	ds_read_b64_tr_b16 v[216:217], v150 offset:6656
	ds_read_b64_tr_b16 v[218:219], v150 offset:7168
	ds_read_b64_tr_b16 v[220:221], v150 offset:7680
	s_add_i32 s7, s6, 0x6000
	s_mov_b32 m0, s6
	global_load_lds_dwordx4 v[6:7], off
	s_mov_b32 m0, s7
	global_load_lds_dwordx4 v[8:9], off
	s_add_i32 s6, s15, -1
	s_cmp_lt_u32 s35, 63
	s_cselect_b32 s10, s6, 63
	s_lshl_b64 s[6:7], s[10:11], 15
	v_lshl_add_u64 v[6:7], v[136:137], 0, s[6:7]
	global_load_dwordx2 v[138:139], v[6:7], off
	s_waitcnt lgkmcnt(0)
	s_barrier
	v_mfma_f32_32x32x16_bf16 v[66:81], v[182:185], v[110:113], v[66:81]
	v_mfma_f32_32x32x16_bf16 v[66:81], v[186:189], v[98:101], v[66:81]
	v_mfma_f32_32x32x16_bf16 v[66:81], v[190:193], v[102:105], v[66:81]
	v_mfma_f32_32x32x16_bf16 v[66:81], v[194:197], v[106:109], v[66:81]
	s_cmp_lt_u32 s33, s14
	s_cbranch_scc0 .Lpp_bias
	v_mfma_f32_32x32x16_bf16 v[82:97], v[198:201], v[110:113], v[82:97]
	s_add_i32 s5, s34, 1
	s_cmp_lg_u32 s34, 2
	s_cselect_b32 s34, s5, 0
	v_mfma_f32_32x32x16_bf16 v[82:97], v[202:205], v[98:101], v[82:97]
	s_addk_i32 s31, 0xff00
	s_add_i32 s15, s15, 1
	s_add_i32 s5, s30, s31
	v_mfma_f32_32x32x16_bf16 v[82:97], v[206:209], v[102:105], v[82:97]
	s_add_i32 s33, s33, 64
	s_cmp_eq_u32 s5, 0
	s_cselect_b32 s37, 1, 0
	v_exp_f32_e32 v66, v66
	v_exp_f32_e32 v67, v67
	v_exp_f32_e32 v68, v68
	v_mfma_f32_32x32x16_bf16 v[82:97], v[210:213], v[106:109], v[82:97]
	v_exp_f32_e32 v69, v69
	v_exp_f32_e32 v70, v70
	v_exp_f32_e32 v71, v71
	v_exp_f32_e32 v72, v72
	v_exp_f32_e32 v73, v73
	v_cvt_pk_bf16_f32 v4, v66, v67
	v_cvt_pk_bf16_f32 v5, v68, v69
	v_cvt_pk_bf16_f32 v6, v70, v71
	v_cvt_pk_bf16_f32 v7, v72, v73
	v_exp_f32_e32 v74, v74
	v_exp_f32_e32 v75, v75
	v_mfma_f32_32x32x16_bf16 v[34:49], v[4:7], v[152:155], v[34:49]
	v_exp_f32_e32 v76, v76
	v_exp_f32_e32 v77, v77
	v_exp_f32_e32 v78, v78
	v_mfma_f32_32x32x16_bf16 v[18:33], v[4:7], v[168:171], v[18:33]
	v_exp_f32_e32 v79, v79
	v_exp_f32_e32 v80, v80
	v_exp_f32_e32 v81, v81
	v_mfma_f32_32x32x16_bf16 v[50:65], v[4:7], v[226:229], v[50:65]
	v_cvt_pk_bf16_f32 v8, v74, v75
	v_cvt_pk_bf16_f32 v9, v76, v77
	v_cvt_pk_bf16_f32 v10, v78, v79
	v_cvt_pk_bf16_f32 v11, v80, v81
	v_exp_f32_e32 v82, v82
	v_exp_f32_e32 v83, v83
	v_mfma_f32_32x32x16_bf16 v[34:49], v[8:11], v[156:159], v[34:49]
	v_exp_f32_e32 v84, v84
	v_exp_f32_e32 v85, v85
	v_exp_f32_e32 v86, v86
	v_mfma_f32_32x32x16_bf16 v[18:33], v[8:11], v[172:175], v[18:33]
	v_exp_f32_e32 v87, v87
	v_exp_f32_e32 v88, v88
	v_exp_f32_e32 v89, v89
	v_mfma_f32_32x32x16_bf16 v[50:65], v[8:11], v[226:229], v[50:65]
	v_cvt_pk_bf16_f32 v12, v82, v83
	v_cvt_pk_bf16_f32 v13, v84, v85
	v_cvt_pk_bf16_f32 v14, v86, v87
	v_cvt_pk_bf16_f32 v15, v88, v89
	v_exp_f32_e32 v90, v90
	v_exp_f32_e32 v91, v91
	v_mfma_f32_32x32x16_bf16 v[34:49], v[12:15], v[160:163], v[34:49]
	v_exp_f32_e32 v92, v92
	v_exp_f32_e32 v93, v93
	v_exp_f32_e32 v94, v94
	s_add_i32 s35, s15, -2
	s_lshl_b32 s5, s34, 13
	s_cmp_lt_u32 s15, s27
	s_cselect_b32 s10, s15, s29
	v_mfma_f32_32x32x16_bf16 v[18:33], v[12:15], v[214:217], v[18:33]
	v_exp_f32_e32 v95, v95
	v_exp_f32_e32 v96, v96
	v_exp_f32_e32 v97, v97
	s_lshl_b64 s[6:7], s[10:11], 16
	s_waitcnt vmcnt(0)
	v_mfma_f32_32x32x16_bf16 v[50:65], v[12:15], v[226:229], v[50:65]
	v_cvt_pk_bf16_f32 v222, v90, v91
	v_cvt_pk_bf16_f32 v223, v92, v93
	v_cvt_pk_bf16_f32 v224, v94, v95
	v_cvt_pk_bf16_f32 v225, v96, v97
	v_lshl_add_u64 v[6:7], v[116:117], 0, s[6:7]
	v_lshl_add_u64 v[8:9], v[118:119], 0, s[6:7]
	v_mfma_f32_32x32x16_bf16 v[34:49], v[222:225], v[164:167], v[34:49]
	v_lshrrev_b32_e32 v3, v1, v138
	s_add_i32 s6, s5, 0xffffe000
	v_lshlrev_b32_e32 v3, 4, v3
	s_cmp_lg_u32 s34, 0
	v_and_b32_e32 v4, 0xf0f0f0f0, v3
	v_mfma_f32_32x32x16_bf16 v[18:33], v[222:225], v[218:221], v[18:33]
	v_lshrrev_b32_e32 v3, v1, v139
	s_cselect_b32 s6, s6, 0x4000
	v_lshlrev_b32_e32 v3, 4, v3
	s_add_i32 s6, s20, s6
	v_and_b32_e32 v3, 0xf0f0f0f0, v3
	v_mfma_f32_32x32x16_bf16 v[50:65], v[222:225], v[226:229], v[50:65]
	s_cmp_lg_u32 s37, 0
	s_cbranch_scc1 .LBB0_946
	s_branch .Lpp_hb
